# SSD conv: conv weights staged in LDS, next iteration row loads prefetched after unpack; cq norm loop: loads up front, DPP wave sum
# speedup vs baseline: 1.0148x; 1.0013x over previous
.LBB0_151:
	s_and_b64 vcc, exec, s[4:5]
	s_cbranch_vccz .LBB0_314
	s_cmp_gt_i32 s0, 0
	s_mov_b64 s[4:5], -1
	s_cbranch_scc0 .LBB0_312
	s_cmp_gt_i32 s0, 1
	s_cbranch_scc0 .LBB0_254
	s_lshr_b32 s3, s64, 6
	s_mul_i32 s3, s3, 48
	s_cmp_ge_i32 s2, s3
	s_cbranch_scc1 .LBB0_253
	s_waitcnt vmcnt(0)
	v_ashrrev_i32_e32 v54, 3, v160
	s_movk_i32 s4, 0x8c
	v_and_b32_e32 v4, 7, v218
	v_mul_lo_u32 v0, v54, s4
	s_load_dwordx4 s[8:11], s[82:83], 0x60
	s_load_dwordx2 s[16:17], s[82:83], 0x18
	v_add_u32_e32 v5, 0, v0
	v_lshlrev_b32_e32 v0, 4, v4
	s_add_u32 s6, s54, 0x10380000
	v_lshl_add_u64 v[2:3], s[54:55], 0, v[0:1]
	s_mov_b64 s[4:5], 0x1cbc0000
	s_addc_u32 s7, s55, 0
	v_lshl_add_u64 v[58:59], v[2:3], 0, s[4:5]
	s_mov_b64 s[4:5], 0x171c0000
	s_add_u32 s14, s54, 0x1ddc0000
	v_ashrrev_i32_e32 v55, 31, v54
	v_lshl_add_u64 v[60:61], v[2:3], 0, s[4:5]
	v_mul_u32_u24_e32 v2, 0x460, v4
	v_lshlrev_b32_e32 v3, 1, v54
	s_addc_u32 s15, s55, 0
	s_add_i32 s42, s3, -1
	v_lshlrev_b32_e32 v56, 3, v4
	v_add_u32_e32 v57, -3, v54
	v_add3_u32 v120, 0, v2, v3
	v_lshlrev_b64 v[62:63], 7, v[54:55]
	s_lshl_b32 s43, s76, 1
	v_add_u32_e32 v121, v5, v0
	s_mov_b32 s46, s2
	s_waitcnt lgkmcnt(0)
	v_lshlrev_b32_e32 v228, 4, v160
	v_add_u32_e32 v230, 0x8000, v228
	global_load_dwordx4 v[142:145], v228, s[8:9]
	v_add_u32_e32 v229, 0x2000, v228
	global_load_dwordx4 v[146:149], v229, s[8:9]
	v_add_u32_e32 v229, 0x4000, v228
	global_load_dwordx4 v[150:153], v229, s[8:9]
	v_add_u32_e32 v229, 0x6000, v228
	global_load_dwordx4 v[162:165], v229, s[8:9]
	v_add_u32_e32 v229, 0x8000, v228
	global_load_dwordx4 v[166:169], v229, s[8:9]
	v_add_u32_e32 v229, 0xa000, v228
	global_load_dwordx4 v[170:173], v229, s[8:9]
	global_load_dwordx4 v[174:177], v228, s[10:11]
	v_cmp_gt_u32_e32 vcc, 0x100, v160
	s_and_saveexec_b64 s[98:99], vcc
	v_add_u32_e32 v229, 0x2000, v228
	global_load_dwordx4 v[178:181], v229, s[10:11]
	s_waitcnt vmcnt(0)
	ds_write_b128 v230, v[178:181] offset:57344
	s_mov_b64 exec, s[98:99]
	ds_write_b128 v230, v[142:145]
	ds_write_b128 v230, v[146:149] offset:8192
	ds_write_b128 v230, v[150:153] offset:16384
	ds_write_b128 v230, v[162:165] offset:24576
	ds_write_b128 v230, v[166:169] offset:32768
	ds_write_b128 v230, v[170:173] offset:40960
	ds_write_b128 v230, v[174:177] offset:49152
	s_waitcnt lgkmcnt(0)
	s_barrier
	s_mov_b64 s[74:75], 0x1800
	s_min_i32 s32, s46, s42
	s_mul_hi_i32 s47, s32, 0x2aaaaaab
	s_lshr_b32 s50, s47, 31
	s_ashr_i32 s47, s47, 3
	s_add_i32 s47, s47, s50
	s_mul_i32 s50, s47, 0xffffffd0
	s_add_i32 s50, s50, s32
	s_lshl_b32 s47, s47, 6
	s_lshl_b32 s50, s50, 6
	v_or_b32_e32 v228, s50, v56
	v_mov_b32_e32 v229, 0
	v_lshl_add_u64 v[228:229], v[228:229], 1, s[6:7]
	v_add_u32_e32 v232, s47, v57
	v_mad_i64_i32 v[230:231], s[98:99], v232, s67, v[228:229]
	global_load_dwordx4 v[142:145], v[230:231], off
	v_lshl_add_u64 v[230:231], v[230:231], 0, s[74:75]
	global_load_dwordx4 v[146:149], v[230:231], off
	v_lshl_add_u64 v[230:231], v[230:231], 0, s[74:75]
	global_load_dwordx4 v[150:153], v[230:231], off
	v_lshl_add_u64 v[230:231], v[230:231], 0, s[74:75]
	global_load_dwordx4 v[162:165], v[230:231], off
	s_add_i32 s32, s46, s76
	s_min_i32 s32, s32, s42
	s_mul_hi_i32 s47, s32, 0x2aaaaaab
	s_lshr_b32 s50, s47, 31
	s_ashr_i32 s47, s47, 3
	s_add_i32 s47, s47, s50
	s_mul_i32 s50, s47, 0xffffffd0
	s_add_i32 s50, s50, s32
	s_lshl_b32 s47, s47, 6
	s_lshl_b32 s50, s50, 6
	v_or_b32_e32 v228, s50, v56
	v_mov_b32_e32 v229, 0
	v_lshl_add_u64 v[228:229], v[228:229], 1, s[6:7]
	v_add_u32_e32 v232, s47, v57
	v_mad_i64_i32 v[230:231], s[98:99], v232, s67, v[228:229]
	global_load_dwordx4 v[166:169], v[230:231], off
	v_lshl_add_u64 v[230:231], v[230:231], 0, s[74:75]
	global_load_dwordx4 v[170:173], v[230:231], off
	v_lshl_add_u64 v[230:231], v[230:231], 0, s[74:75]
	global_load_dwordx4 v[174:177], v[230:231], off
	v_lshl_add_u64 v[230:231], v[230:231], 0, s[74:75]
	global_load_dwordx4 v[178:181], v[230:231], off
	s_add_i32 s32, s46, s43
	s_min_i32 s32, s32, s42
	s_mul_hi_i32 s47, s32, 0x2aaaaaab
	s_lshr_b32 s50, s47, 31
	s_ashr_i32 s47, s47, 3
	s_add_i32 s47, s47, s50
	s_mul_i32 s50, s47, 0xffffffd0
	s_add_i32 s50, s50, s32
	s_lshl_b32 s47, s47, 6
	s_lshl_b32 s50, s50, 6
	v_or_b32_e32 v228, s50, v56
	v_mov_b32_e32 v229, 0
	v_lshl_add_u64 v[228:229], v[228:229], 1, s[6:7]
	v_add_u32_e32 v232, s47, v57
	v_mad_i64_i32 v[230:231], s[98:99], v232, s67, v[228:229]
	global_load_dwordx4 v[182:185], v[230:231], off
	v_lshl_add_u64 v[230:231], v[230:231], 0, s[74:75]
	global_load_dwordx4 v[186:189], v[230:231], off
	v_lshl_add_u64 v[230:231], v[230:231], 0, s[74:75]
	global_load_dwordx4 v[220:223], v[230:231], off
	v_lshl_add_u64 v[230:231], v[230:231], 0, s[74:75]
	global_load_dwordx4 v[224:227], v[230:231], off
	v_mov_b32_e32 v235, 0
	global_load_dword v234, v235, s[10:11]
	global_load_dword v234, v235, s[10:11]
	global_load_dword v234, v235, s[10:11]
	global_load_dword v234, v235, s[10:11]
	global_load_dword v234, v235, s[10:11]
	global_load_dword v234, v235, s[10:11]
	s_branch .LBB0_158

.LBB0_161:
	s_or_saveexec_b64 s[26:27], s[26:27]
	v_add_u32_e32 v0, s19, v57
	s_waitcnt vmcnt(17)
	v_lshl_add_u64 v[6:7], v[52:53], 1, s[6:7]
	s_xor_b64 exec, exec, s[26:27]
	s_cbranch_execz .LBB0_163
	v_mad_i64_i32 v[8:9], s[28:29], v0, s67, v[6:7]
	s_waitcnt vmcnt(17)
	s_nop 0
	v_lshlrev_b32_e32 v38, 16, v142
	v_and_b32_e32 v106, 0xffff0000, v142
	v_lshlrev_b32_e32 v40, 16, v143
	v_and_b32_e32 v100, 0xffff0000, v143
	v_lshlrev_b32_e32 v103, 16, v144
	v_and_b32_e32 v11, 0xffff0000, v144
	v_lshlrev_b32_e32 v99, 16, v145
	v_and_b32_e32 v13, 0xffff0000, v145

.LBB0_166:
	s_andn2_saveexec_b64 s[26:27], s[26:27]
	s_cbranch_execz .LBB0_168
	v_add_u32_e32 v3, 1, v0
	v_mad_i64_i32 v[8:9], s[28:29], v3, s67, v[6:7]
	s_waitcnt vmcnt(16)
	s_nop 0
	v_lshlrev_b32_e32 v39, 16, v146
	v_and_b32_e32 v107, 0xffff0000, v146
	v_lshlrev_b32_e32 v41, 16, v147
	v_and_b32_e32 v101, 0xffff0000, v147
	v_lshlrev_b32_e32 v102, 16, v148
	v_and_b32_e32 v10, 0xffff0000, v148
	v_lshlrev_b32_e32 v98, 16, v149
	v_and_b32_e32 v12, 0xffff0000, v149

.LBB0_171:
.LBB0_172:
	s_andn2_saveexec_b64 s[26:27], s[26:27]
	s_cbranch_execz .LBB0_174
	v_add_u32_e32 v0, 2, v0
	v_mad_i64_i32 v[8:9], s[28:29], v0, s67, v[6:7]
	s_waitcnt vmcnt(15)
	s_nop 0
	v_lshlrev_b32_e32 v46, 16, v150
	v_and_b32_e32 v112, 0xffff0000, v150
	v_lshlrev_b32_e32 v48, 16, v151
	v_and_b32_e32 v108, 0xffff0000, v151
	v_lshlrev_b32_e32 v111, 16, v152
	v_and_b32_e32 v43, 0xffff0000, v152
	v_lshlrev_b32_e32 v105, 16, v153
	v_and_b32_e32 v45, 0xffff0000, v153

.LBB0_177:
.LBB0_178:
	s_andn2_saveexec_b64 s[4:5], s[26:27]
	s_cbranch_execz .LBB0_180
	v_add_u32_e32 v0, s19, v54
	v_mad_i64_i32 v[2:3], s[24:25], v0, s67, v[6:7]
	s_waitcnt vmcnt(14)
	s_nop 0
	v_lshlrev_b32_e32 v47, 16, v162
	v_and_b32_e32 v113, 0xffff0000, v162
	v_lshlrev_b32_e32 v49, 16, v163
	v_and_b32_e32 v109, 0xffff0000, v163
	v_lshlrev_b32_e32 v110, 16, v164
	v_and_b32_e32 v42, 0xffff0000, v164
	v_lshlrev_b32_e32 v104, 16, v165
	v_and_b32_e32 v44, 0xffff0000, v165

.LBB0_183:
	s_or_saveexec_b64 s[34:35], s[34:35]
	v_add_u32_e32 v0, s25, v57
	v_lshl_add_u64 v[6:7], v[50:51], 1, s[6:7]
	s_xor_b64 exec, exec, s[34:35]
	s_cbranch_execz .LBB0_185
	v_mad_i64_i32 v[8:9], s[36:37], v0, s67, v[6:7]
	s_waitcnt vmcnt(13)
	s_nop 0
	v_lshlrev_b32_e32 v34, 16, v166
	v_and_b32_e32 v96, 0xffff0000, v166
	v_lshlrev_b32_e32 v36, 16, v167
	v_and_b32_e32 v92, 0xffff0000, v167
	v_lshlrev_b32_e32 v95, 16, v168
	v_and_b32_e32 v31, 0xffff0000, v168
	v_lshlrev_b32_e32 v91, 16, v169
	v_and_b32_e32 v33, 0xffff0000, v169

.LBB0_188:
	s_andn2_saveexec_b64 s[34:35], s[34:35]
	s_cbranch_execz .LBB0_190
	v_add_u32_e32 v3, 1, v0
	v_mad_i64_i32 v[8:9], s[36:37], v3, s67, v[6:7]
	s_waitcnt vmcnt(12)
	s_nop 0
	v_lshlrev_b32_e32 v35, 16, v170
	v_and_b32_e32 v97, 0xffff0000, v170
	v_lshlrev_b32_e32 v37, 16, v171
	v_and_b32_e32 v93, 0xffff0000, v171
	v_lshlrev_b32_e32 v94, 16, v172
	v_and_b32_e32 v30, 0xffff0000, v172
	v_lshlrev_b32_e32 v90, 16, v173
	v_and_b32_e32 v32, 0xffff0000, v173

.LBB0_193:
.LBB0_194:
	s_andn2_saveexec_b64 s[34:35], s[34:35]
	s_cbranch_execz .LBB0_196
	v_add_u32_e32 v0, 2, v0
	v_mad_i64_i32 v[8:9], s[36:37], v0, s67, v[6:7]
	s_waitcnt vmcnt(11)
	s_nop 0
	v_lshlrev_b32_e32 v26, 16, v174
	v_and_b32_e32 v86, 0xffff0000, v174
	v_lshlrev_b32_e32 v28, 16, v175
	v_and_b32_e32 v84, 0xffff0000, v175
	v_lshlrev_b32_e32 v89, 16, v176
	v_and_b32_e32 v23, 0xffff0000, v176
	v_lshlrev_b32_e32 v83, 16, v177
	v_and_b32_e32 v25, 0xffff0000, v177

.LBB0_199:
.LBB0_200:
	s_andn2_saveexec_b64 s[4:5], s[34:35]
	s_cbranch_execz .LBB0_202
	v_add_u32_e32 v0, s25, v54
	v_mad_i64_i32 v[2:3], s[30:31], v0, s67, v[6:7]
	s_waitcnt vmcnt(10)
	s_nop 0
	v_lshlrev_b32_e32 v27, 16, v178
	v_and_b32_e32 v87, 0xffff0000, v178
	v_lshlrev_b32_e32 v29, 16, v179
	v_and_b32_e32 v85, 0xffff0000, v179
	v_lshlrev_b32_e32 v88, 16, v180
	v_and_b32_e32 v22, 0xffff0000, v180
	v_lshlrev_b32_e32 v82, 16, v181
	v_and_b32_e32 v24, 0xffff0000, v181

.LBB0_205:
	s_or_saveexec_b64 s[40:41], s[40:41]
	v_add_u32_e32 v0, s31, v57
	v_lshl_add_u64 v[118:119], v[76:77], 1, s[6:7]
	s_xor_b64 exec, exec, s[40:41]
	s_cbranch_execz .LBB0_207
	v_mad_i64_i32 v[2:3], s[48:49], v0, s67, v[118:119]
	s_waitcnt vmcnt(9)
	s_nop 0
	v_lshlrev_b32_e32 v18, 16, v182
	v_and_b32_e32 v80, 0xffff0000, v182
	v_lshlrev_b32_e32 v20, 16, v183
	v_and_b32_e32 v74, 0xffff0000, v183
	v_lshlrev_b32_e32 v79, 16, v184
	v_and_b32_e32 v15, 0xffff0000, v184
	v_lshlrev_b32_e32 v73, 16, v185
	v_and_b32_e32 v17, 0xffff0000, v185

.LBB0_210:
	s_andn2_saveexec_b64 s[40:41], s[40:41]
	s_cbranch_execz .LBB0_212
	v_add_u32_e32 v2, 1, v0
	v_mad_i64_i32 v[2:3], s[48:49], v2, s67, v[118:119]
	s_waitcnt vmcnt(8)
	s_nop 0
	v_lshlrev_b32_e32 v19, 16, v186
	v_and_b32_e32 v81, 0xffff0000, v186
	v_lshlrev_b32_e32 v21, 16, v187
	v_and_b32_e32 v75, 0xffff0000, v187
	v_lshlrev_b32_e32 v78, 16, v188
	v_and_b32_e32 v14, 0xffff0000, v188
	v_lshlrev_b32_e32 v72, 16, v189
	v_and_b32_e32 v16, 0xffff0000, v189

.LBB0_215:
.LBB0_216:
	s_andn2_saveexec_b64 s[40:41], s[40:41]
	s_cbranch_execz .LBB0_218
	v_add_u32_e32 v0, 2, v0
	v_mad_i64_i32 v[2:3], s[48:49], v0, s67, v[118:119]
	s_waitcnt vmcnt(7)
	s_nop 0
	v_lshlrev_b32_e32 v6, 16, v220
	v_and_b32_e32 v68, 0xffff0000, v220
	v_lshlrev_b32_e32 v8, 16, v221
	v_and_b32_e32 v64, 0xffff0000, v221
	v_lshlrev_b32_e32 v71, 16, v222
	v_and_b32_e32 v3, 0xffff0000, v222
	v_lshlrev_b32_e32 v67, 16, v223
	v_and_b32_e32 v5, 0xffff0000, v223

.LBB0_221:
.LBB0_222:
	s_andn2_saveexec_b64 s[4:5], s[40:41]
	s_cbranch_execz .LBB0_224
	v_add_u32_e32 v0, s31, v54
	v_mad_i64_i32 v[114:115], s[38:39], v0, s67, v[118:119]
	s_waitcnt vmcnt(6)
	s_nop 0
	v_lshlrev_b32_e32 v7, 16, v224
	v_and_b32_e32 v69, 0xffff0000, v224
	v_lshlrev_b32_e32 v9, 16, v225
	v_and_b32_e32 v65, 0xffff0000, v225
	v_lshlrev_b32_e32 v70, 16, v226
	v_and_b32_e32 v2, 0xffff0000, v226
	v_lshlrev_b32_e32 v66, 16, v227
	v_and_b32_e32 v4, 0xffff0000, v227
.LBB0_224:
	s_or_b64 exec, exec, s[4:5]
	s_mov_b64 s[74:75], 0x1800
	s_mul_i32 s32, s76, 3
	s_add_i32 s32, s32, s46
	s_min_i32 s32, s32, s42
	s_mul_hi_i32 s47, s32, 0x2aaaaaab
	s_lshr_b32 s50, s47, 31
	s_ashr_i32 s47, s47, 3
	s_add_i32 s47, s47, s50
	s_mul_i32 s50, s47, 0xffffffd0
	s_add_i32 s50, s50, s32
	s_lshl_b32 s47, s47, 6
	s_lshl_b32 s50, s50, 6
	v_or_b32_e32 v228, s50, v56
	v_mov_b32_e32 v229, 0
	v_lshl_add_u64 v[228:229], v[228:229], 1, s[6:7]
	v_add_u32_e32 v232, s47, v57
	v_mad_i64_i32 v[230:231], s[98:99], v232, s67, v[228:229]
	global_load_dwordx4 v[142:145], v[230:231], off
	v_lshl_add_u64 v[230:231], v[230:231], 0, s[74:75]
	global_load_dwordx4 v[146:149], v[230:231], off
	v_lshl_add_u64 v[230:231], v[230:231], 0, s[74:75]
	global_load_dwordx4 v[150:153], v[230:231], off
	v_lshl_add_u64 v[230:231], v[230:231], 0, s[74:75]
	global_load_dwordx4 v[162:165], v[230:231], off
	s_mul_i32 s32, s76, 4
	s_add_i32 s32, s32, s46
	s_min_i32 s32, s32, s42
	s_mul_hi_i32 s47, s32, 0x2aaaaaab
	s_lshr_b32 s50, s47, 31
	s_ashr_i32 s47, s47, 3
	s_add_i32 s47, s47, s50
	s_mul_i32 s50, s47, 0xffffffd0
	s_add_i32 s50, s50, s32
	s_lshl_b32 s47, s47, 6
	s_lshl_b32 s50, s50, 6
	v_or_b32_e32 v228, s50, v56
	v_mov_b32_e32 v229, 0
	v_lshl_add_u64 v[228:229], v[228:229], 1, s[6:7]
	v_add_u32_e32 v232, s47, v57
	v_mad_i64_i32 v[230:231], s[98:99], v232, s67, v[228:229]
	global_load_dwordx4 v[166:169], v[230:231], off
	v_lshl_add_u64 v[230:231], v[230:231], 0, s[74:75]
	global_load_dwordx4 v[170:173], v[230:231], off
	v_lshl_add_u64 v[230:231], v[230:231], 0, s[74:75]
	global_load_dwordx4 v[174:177], v[230:231], off
	v_lshl_add_u64 v[230:231], v[230:231], 0, s[74:75]
	global_load_dwordx4 v[178:181], v[230:231], off
	s_mul_i32 s32, s76, 5
	s_add_i32 s32, s32, s46
	s_min_i32 s32, s32, s42
	s_mul_hi_i32 s47, s32, 0x2aaaaaab
	s_lshr_b32 s50, s47, 31
	s_ashr_i32 s47, s47, 3
	s_add_i32 s47, s47, s50
	s_mul_i32 s50, s47, 0xffffffd0
	s_add_i32 s50, s50, s32
	s_lshl_b32 s47, s47, 6
	s_lshl_b32 s50, s50, 6
	v_or_b32_e32 v228, s50, v56
	v_mov_b32_e32 v229, 0
	v_lshl_add_u64 v[228:229], v[228:229], 1, s[6:7]
	v_add_u32_e32 v232, s47, v57
	v_mad_i64_i32 v[230:231], s[98:99], v232, s67, v[228:229]
	global_load_dwordx4 v[182:185], v[230:231], off
	v_lshl_add_u64 v[230:231], v[230:231], 0, s[74:75]
	global_load_dwordx4 v[186:189], v[230:231], off
	v_lshl_add_u64 v[230:231], v[230:231], 0, s[74:75]
	global_load_dwordx4 v[220:223], v[230:231], off
	v_lshl_add_u64 v[230:231], v[230:231], 0, s[74:75]
	global_load_dwordx4 v[224:227], v[230:231], off
	v_mov_b32_e32 v235, 0
	global_load_dword v234, v235, s[10:11]
	global_load_dword v234, v235, s[10:11]
	global_load_dword v234, v235, s[10:11]
	global_load_dword v234, v235, s[10:11]
	global_load_dword v234, v235, s[10:11]
	global_load_dword v234, v235, s[10:11]
	v_lshlrev_b64 v[52:53], 2, v[52:53]
	v_add_u32_e32 v233, 0x8000, v52
	v_lshl_add_u64 v[118:119], s[10:11], 0, v[52:53]
	v_lshl_add_u64 v[52:53], s[8:9], 0, v[52:53]
	v_add_co_u32_e32 v134, vcc, s86, v52
	ds_read_b128 v[114:117], v233 offset:49168
	ds_read_b128 v[122:125], v233 offset:49152
	ds_read_b128 v[126:129], v233 offset:16
	ds_read_b128 v[130:133], v233
	s_mov_b64 s[38:39], 0x3000
	v_addc_co_u32_e32 v135, vcc, 0, v53, vcc
	v_lshl_add_u64 v[118:119], v[52:53], 0, s[38:39]
	ds_read_b128 v[134:137], v233 offset:12288
	s_nop 0
	ds_read_b128 v[138:141], v233 offset:12304
	s_movk_i32 s4, 0x6000
	s_mov_b64 s[40:41], 0x6000
	s_mov_b64 s[48:49], 0x9000
	s_mov_b32 s5, 0x9000
	s_cmp_lt_i32 s20, 40
	s_waitcnt lgkmcnt(2)
	v_mov_b32_e32 v118, v130
	s_waitcnt lgkmcnt(1)
	v_mov_b32_e32 v119, v134
	v_pk_mul_f32 v[38:39], v[118:119], v[38:39]
	v_mov_b32_e32 v134, v131
	v_add_f32_e32 v0, v122, v38
	v_add_f32_e32 v0, v0, v39
	s_waitcnt lgkmcnt(0)
	v_mov_b32_e32 v38, v138
	v_mov_b32_e32 v39, v126
	v_mov_b32_e32 v126, v139
	v_pk_mul_f32 v[38:39], v[38:39], v[102:103]
	v_pk_mul_f32 v[10:11], v[126:127], v[10:11]
	v_add_f32_e32 v39, v39, v114
	v_add_f32_e32 v11, v11, v115
	v_add_f32_e32 v118, v38, v39
	v_pk_mul_f32 v[38:39], v[134:135], v[106:107]
	v_add_f32_e32 v107, v10, v11
	v_mov_b32_e32 v10, v132
	v_mov_b32_e32 v11, v136
	v_pk_mul_f32 v[10:11], v[10:11], v[40:41]
	v_mov_b32_e32 v136, v133
	v_add_f32_e32 v10, v124, v10
	v_add_f32_e32 v119, v10, v11
	v_mov_b32_e32 v10, v140
	v_mov_b32_e32 v11, v128
	v_pk_mul_f32 v[10:11], v[10:11], v[98:99]
	v_mov_b32_e32 v128, v141
	v_add_f32_e32 v11, v11, v116
	v_add_f32_e32 v122, v10, v11
	v_pk_mul_f32 v[10:11], v[136:137], v[100:101]
	v_add_f32_e32 v38, v123, v38
	v_add_f32_e32 v10, v125, v10
	v_add_f32_e32 v123, v10, v11
	v_pk_mul_f32 v[10:11], v[128:129], v[12:13]
	v_add_f32_e32 v106, v38, v39
	v_add_f32_e32 v11, v11, v117
	v_add_f32_e32 v124, v10, v11
	v_add_co_u32_e32 v10, vcc, s4, v52
	v_lshl_add_u64 v[38:39], v[52:53], 0, s[40:41]
	s_nop 0
	v_addc_co_u32_e32 v11, vcc, 0, v53, vcc
	v_lshl_add_u64 v[102:103], v[52:53], 0, s[48:49]
	v_add_co_u32_e32 v52, vcc, s5, v52
	ds_read_b128 v[10:13], v233 offset:24576
	s_nop 0
	ds_read_b128 v[38:41], v233 offset:24592
	v_addc_co_u32_e32 v53, vcc, 0, v53, vcc
	ds_read_b128 v[98:101], v233 offset:36864
	ds_read_b128 v[114:117], v233 offset:36880
	s_waitcnt lgkmcnt(3)
	v_mov_b32_e32 v52, v10
	s_waitcnt lgkmcnt(1)
	v_mov_b32_e32 v53, v98
	v_pk_mul_f32 v[46:47], v[52:53], v[46:47]
	v_mov_b32_e32 v98, v11
	v_add_f32_e32 v0, v0, v46
	v_add_f32_e32 v0, v0, v47
	s_waitcnt lgkmcnt(0)
	v_mov_b32_e32 v46, v114
	v_mov_b32_e32 v47, v38
	v_pk_mul_f32 v[46:47], v[46:47], v[110:111]
	v_mov_b32_e32 v38, v115
	v_add_f32_e32 v10, v47, v118
	v_add_f32_e32 v46, v46, v10
	v_pk_mul_f32 v[10:11], v[98:99], v[112:113]
	s_nop 0
	v_add_f32_e32 v10, v106, v10
	v_add_f32_e32 v47, v10, v11
	v_pk_mul_f32 v[10:11], v[38:39], v[42:43]
	s_nop 0
	v_add_f32_e32 v11, v11, v107
	v_add_f32_e32 v38, v10, v11
	v_mov_b32_e32 v10, v12
	v_mov_b32_e32 v11, v100
	v_pk_mul_f32 v[10:11], v[10:11], v[48:49]
	v_mov_b32_e32 v100, v13
	v_add_f32_e32 v10, v119, v10
	v_add_f32_e32 v12, v10, v11
	v_mov_b32_e32 v10, v116
	v_mov_b32_e32 v11, v40
	v_pk_mul_f32 v[10:11], v[10:11], v[104:105]
	v_mov_b32_e32 v40, v117
	v_add_f32_e32 v11, v11, v122
	v_add_f32_e32 v39, v10, v11
	v_pk_mul_f32 v[10:11], v[100:101], v[108:109]
	s_nop 0
	v_add_f32_e32 v10, v123, v10
	v_add_f32_e32 v13, v10, v11
	v_pk_mul_f32 v[10:11], v[40:41], v[44:45]
	v_mul_f32_e32 v40, 0xbfb8aa3b, v12
	v_exp_f32_e32 v40, v40
	v_mul_f32_e32 v41, 0xbfb8aa3b, v38
	v_exp_f32_e32 v41, v41
	v_add_f32_e32 v11, v11, v124
	v_add_f32_e32 v40, 1.0, v40
	v_rcp_f32_e32 v40, v40
	v_add_f32_e32 v41, 1.0, v41
	v_rcp_f32_e32 v41, v41
	v_add_f32_e32 v10, v10, v11
	v_mul_f32_e32 v11, 0xbfb8aa3b, v0
	v_mul_f32_e32 v12, v12, v40
	v_mul_f32_e32 v40, 0xbfb8aa3b, v13
	v_exp_f32_e32 v11, v11
	v_exp_f32_e32 v40, v40
	v_mul_f32_e32 v38, v38, v41
	v_mul_f32_e32 v41, 0xbfb8aa3b, v39
	v_exp_f32_e32 v41, v41
	v_add_f32_e32 v11, 1.0, v11
	v_add_f32_e32 v40, 1.0, v40
	v_rcp_f32_e32 v11, v11
	v_rcp_f32_e32 v40, v40
	v_add_f32_e32 v41, 1.0, v41
	v_rcp_f32_e32 v41, v41
	v_mul_f32_e32 v0, v0, v11
	v_mul_f32_e32 v11, 0xbfb8aa3b, v47
	v_mul_f32_e32 v13, v13, v40
	v_mul_f32_e32 v40, 0xbfb8aa3b, v46
	v_exp_f32_e32 v11, v11
	v_exp_f32_e32 v40, v40
	v_mul_f32_e32 v39, v39, v41
	v_mul_f32_e32 v41, 0xbfb8aa3b, v10
	v_exp_f32_e32 v41, v41
	v_add_f32_e32 v11, 1.0, v11
	v_add_f32_e32 v40, 1.0, v40
	v_rcp_f32_e32 v11, v11
	v_rcp_f32_e32 v40, v40
	v_add_f32_e32 v41, 1.0, v41
	v_rcp_f32_e32 v41, v41
	v_mul_f32_e32 v11, v47, v11
	v_mul_f32_e32 v40, v46, v40
	v_lshlrev_b64 v[46:47], 2, v[50:51]
	v_add_u32_e32 v233, 0x8000, v46
	v_lshl_add_u64 v[98:99], s[8:9], 0, v[46:47]
	v_mul_f32_e32 v41, v10, v41
	v_lshl_add_u64 v[42:43], s[10:11], 0, v[46:47]
	v_add_co_u32_e32 v102, vcc, s86, v98
	v_cvt_pk_bf16_f32 v10, v0, v11
	v_cvt_pk_bf16_f32 v11, v12, v13
	v_cvt_pk_bf16_f32 v12, v40, v38
	v_cvt_pk_bf16_f32 v13, v39, v41
	ds_read_b128 v[38:41], v233 offset:49168
	s_nop 0
	ds_read_b128 v[42:45], v233 offset:49152
	s_nop 0
	ds_read_b128 v[46:49], v233 offset:16
	ds_read_b128 v[50:53], v233
	v_addc_co_u32_e32 v103, vcc, 0, v99, vcc
	v_lshl_add_u64 v[100:101], v[98:99], 0, s[38:39]
	ds_read_b128 v[102:105], v233 offset:12288
	s_nop 0
	ds_read_b128 v[106:109], v233 offset:12304
	s_waitcnt lgkmcnt(2)
	v_mov_b32_e32 v100, v50
	s_waitcnt lgkmcnt(1)
	v_mov_b32_e32 v101, v102
	v_pk_mul_f32 v[34:35], v[100:101], v[34:35]
	v_mov_b32_e32 v102, v51
	v_add_f32_e32 v0, v42, v34
	v_add_f32_e32 v100, v0, v35
	s_waitcnt lgkmcnt(0)
	v_mov_b32_e32 v34, v106
	v_mov_b32_e32 v35, v46
	v_pk_mul_f32 v[34:35], v[34:35], v[94:95]
	v_mov_b32_e32 v46, v107
	v_add_f32_e32 v0, v35, v38
	v_add_f32_e32 v94, v34, v0
	v_pk_mul_f32 v[34:35], v[102:103], v[96:97]
	v_pk_mul_f32 v[30:31], v[46:47], v[30:31]
	v_add_f32_e32 v0, v43, v34
	v_add_f32_e32 v51, v0, v35
	v_add_f32_e32 v0, v31, v39
	v_add_f32_e32 v50, v30, v0
	v_mov_b32_e32 v30, v52
	v_mov_b32_e32 v31, v104
	v_pk_mul_f32 v[30:31], v[30:31], v[36:37]
	v_mov_b32_e32 v104, v53
	v_add_f32_e32 v0, v44, v30
	v_add_f32_e32 v0, v0, v31
	v_mov_b32_e32 v30, v108
	v_mov_b32_e32 v31, v48
	v_pk_mul_f32 v[30:31], v[30:31], v[90:91]
	v_mov_b32_e32 v48, v109
	v_add_f32_e32 v31, v31, v40
	v_add_f32_e32 v46, v30, v31
	v_pk_mul_f32 v[30:31], v[104:105], v[92:93]
	v_lshl_add_u64 v[42:43], v[98:99], 0, s[48:49]
	v_add_f32_e32 v30, v45, v30
	v_add_f32_e32 v47, v30, v31
	v_pk_mul_f32 v[30:31], v[48:49], v[32:33]
	v_add_co_u32_e32 v32, vcc, s4, v98
	v_add_f32_e32 v31, v31, v41
	s_nop 0
	v_addc_co_u32_e32 v33, vcc, 0, v99, vcc
	v_add_co_u32_e32 v38, vcc, s5, v98
	v_add_f32_e32 v48, v30, v31
	v_lshl_add_u64 v[30:31], v[98:99], 0, s[40:41]
	v_addc_co_u32_e32 v39, vcc, 0, v99, vcc
	ds_read_b128 v[34:37], v233 offset:24576
	s_nop 0
	ds_read_b128 v[30:33], v233 offset:24592
	s_nop 0
	ds_read_b128 v[38:41], v233 offset:36864
	s_nop 0
	ds_read_b128 v[42:45], v233 offset:36880
	s_waitcnt lgkmcnt(3)
	v_mov_b32_e32 v52, v34
	s_waitcnt lgkmcnt(1)
	v_mov_b32_e32 v53, v38
	v_pk_mul_f32 v[26:27], v[52:53], v[26:27]
	v_mov_b32_e32 v38, v35
	v_add_f32_e32 v26, v100, v26
	v_add_f32_e32 v34, v26, v27
	s_waitcnt lgkmcnt(0)
	v_mov_b32_e32 v26, v42
	v_mov_b32_e32 v27, v30
	v_pk_mul_f32 v[26:27], v[26:27], v[88:89]
	v_mov_b32_e32 v30, v43
	v_add_f32_e32 v27, v27, v94
	v_add_f32_e32 v42, v26, v27
	v_pk_mul_f32 v[26:27], v[38:39], v[86:87]
	v_pk_mul_f32 v[22:23], v[30:31], v[22:23]
	v_add_f32_e32 v26, v51, v26
	v_add_f32_e32 v23, v23, v50
	v_add_f32_e32 v26, v26, v27
	v_add_f32_e32 v27, v22, v23
	v_mov_b32_e32 v22, v36
	v_mov_b32_e32 v23, v40
	v_pk_mul_f32 v[22:23], v[22:23], v[28:29]
	v_mov_b32_e32 v40, v37
	v_add_f32_e32 v0, v0, v22
	v_add_f32_e32 v0, v0, v23
	v_mov_b32_e32 v22, v44
	v_mov_b32_e32 v23, v32
	v_pk_mul_f32 v[22:23], v[22:23], v[82:83]
	v_mov_b32_e32 v32, v45
	v_add_f32_e32 v23, v23, v46
	v_add_f32_e32 v28, v22, v23
	v_pk_mul_f32 v[22:23], v[40:41], v[84:85]
	s_nop 0
	v_add_f32_e32 v22, v47, v22
	v_add_f32_e32 v29, v22, v23
	v_pk_mul_f32 v[22:23], v[32:33], v[24:25]
	v_mul_f32_e32 v25, 0xbfb8aa3b, v0
	v_exp_f32_e32 v25, v25
	v_mul_f32_e32 v24, 0xbfb8aa3b, v26
	v_exp_f32_e32 v24, v24
	v_add_f32_e32 v23, v23, v48
	v_add_f32_e32 v25, 1.0, v25
	v_rcp_f32_e32 v25, v25
	v_add_f32_e32 v24, 1.0, v24
	v_rcp_f32_e32 v24, v24
	v_add_f32_e32 v22, v22, v23
	v_mul_f32_e32 v0, v0, v25
	v_mul_f32_e32 v25, 0xbfb8aa3b, v29
	v_exp_f32_e32 v25, v25
	v_mul_f32_e32 v24, v26, v24
	v_mul_f32_e32 v26, 0xbfb8aa3b, v42
	v_mul_f32_e32 v23, 0xbfb8aa3b, v34
	v_add_f32_e32 v25, 1.0, v25
	v_rcp_f32_e32 v25, v25
	v_exp_f32_e32 v26, v26
	v_exp_f32_e32 v23, v23
	v_mul_f32_e32 v25, v29, v25
	v_mul_f32_e32 v29, 0xbfb8aa3b, v27
	v_exp_f32_e32 v29, v29
	v_add_f32_e32 v26, 1.0, v26
	v_add_f32_e32 v23, 1.0, v23
	v_rcp_f32_e32 v26, v26
	v_add_f32_e32 v29, 1.0, v29
	v_rcp_f32_e32 v29, v29
	v_rcp_f32_e32 v23, v23
	v_mul_f32_e32 v26, v42, v26
	v_mul_f32_e32 v27, v27, v29
	v_mul_f32_e32 v29, 0xbfb8aa3b, v28
	v_exp_f32_e32 v29, v29
	v_mul_f32_e32 v23, v34, v23
	v_add_f32_e32 v29, 1.0, v29
	v_rcp_f32_e32 v29, v29
	s_nop 0
	v_mul_f32_e32 v28, v28, v29
	v_mul_f32_e32 v29, 0xbfb8aa3b, v22
	v_exp_f32_e32 v29, v29
	s_nop 0
	v_add_f32_e32 v29, 1.0, v29
	v_rcp_f32_e32 v29, v29
	s_nop 0
	v_mul_f32_e32 v29, v22, v29
	v_cvt_pk_bf16_f32 v22, v23, v24
	v_cvt_pk_bf16_f32 v24, v26, v27
	v_lshlrev_b64 v[26:27], 2, v[76:77]
	v_add_u32_e32 v233, 0x8000, v26
	v_lshl_add_u64 v[32:33], s[10:11], 0, v[26:27]
	v_lshl_add_u64 v[26:27], s[8:9], 0, v[26:27]
	v_add_co_u32_e32 v34, vcc, s86, v26
	v_cvt_pk_bf16_f32 v23, v0, v25
	v_cvt_pk_bf16_f32 v25, v28, v29
	ds_read_b128 v[28:31], v233 offset:49168
	ds_read_b128 v[40:43], v233 offset:49152
	ds_read_b128 v[44:47], v233 offset:16
	ds_read_b128 v[48:51], v233
	v_addc_co_u32_e32 v35, vcc, 0, v27, vcc
	v_lshl_add_u64 v[32:33], v[26:27], 0, s[38:39]
	ds_read_b128 v[82:85], v233 offset:12288
	ds_read_b128 v[86:89], v233 offset:12304
	s_waitcnt lgkmcnt(2)
	v_mov_b32_e32 v32, v48
	s_waitcnt lgkmcnt(1)
	v_mov_b32_e32 v33, v82
	v_pk_mul_f32 v[18:19], v[32:33], v[18:19]
	v_mov_b32_e32 v82, v49
	v_add_f32_e32 v0, v40, v18
	v_add_f32_e32 v40, v0, v19
	s_waitcnt lgkmcnt(0)
	v_mov_b32_e32 v18, v86
	v_mov_b32_e32 v19, v44
	v_pk_mul_f32 v[18:19], v[18:19], v[78:79]
	v_mov_b32_e32 v44, v87
	v_add_f32_e32 v0, v19, v28
	v_add_f32_e32 v39, v18, v0
	v_pk_mul_f32 v[18:19], v[82:83], v[80:81]
	v_pk_mul_f32 v[14:15], v[44:45], v[14:15]
	v_add_f32_e32 v0, v41, v18
	v_add_f32_e32 v38, v0, v19
	v_add_f32_e32 v0, v15, v29
	v_add_f32_e32 v37, v14, v0
	v_mov_b32_e32 v14, v50
	v_mov_b32_e32 v15, v84
	v_pk_mul_f32 v[14:15], v[14:15], v[20:21]
	v_mov_b32_e32 v84, v51
	v_add_f32_e32 v0, v42, v14
	v_add_f32_e32 v36, v0, v15
	v_mov_b32_e32 v14, v88
	v_mov_b32_e32 v15, v46
	v_pk_mul_f32 v[14:15], v[14:15], v[72:73]
	v_mov_b32_e32 v46, v89
	v_add_f32_e32 v0, v15, v30
	v_add_f32_e32 v35, v14, v0
	v_pk_mul_f32 v[14:15], v[84:85], v[74:75]
	s_nop 0
	v_add_f32_e32 v0, v43, v14
	v_add_f32_e32 v34, v0, v15
	v_pk_mul_f32 v[14:15], v[46:47], v[16:17]
	v_add_co_u32_e32 v16, vcc, s4, v26
	v_add_f32_e32 v0, v15, v31
	s_nop 0
	v_addc_co_u32_e32 v17, vcc, 0, v27, vcc
	v_add_f32_e32 v0, v14, v0
	v_lshl_add_u64 v[14:15], v[26:27], 0, s[40:41]
	v_lshl_add_u64 v[30:31], v[26:27], 0, s[48:49]
	v_add_co_u32_e32 v26, vcc, s5, v26
	ds_read_b128 v[18:21], v233 offset:24576
	s_nop 0
	ds_read_b128 v[14:17], v233 offset:24592
	v_addc_co_u32_e32 v27, vcc, 0, v27, vcc
	ds_read_b128 v[26:29], v233 offset:36864
	s_nop 0
	ds_read_b128 v[30:33], v233 offset:36880
	s_barrier
	s_waitcnt lgkmcnt(3)
	v_mov_b32_e32 v42, v18
	s_waitcnt lgkmcnt(1)
	v_mov_b32_e32 v43, v26
	v_pk_mul_f32 v[6:7], v[42:43], v[6:7]
	v_mov_b32_e32 v26, v19
	v_add_f32_e32 v6, v40, v6
	v_add_f32_e32 v18, v6, v7
	s_waitcnt lgkmcnt(0)
	v_mov_b32_e32 v6, v30
	v_mov_b32_e32 v7, v14
	v_pk_mul_f32 v[6:7], v[6:7], v[70:71]
	v_mov_b32_e32 v14, v31
	v_add_f32_e32 v7, v7, v39
	v_add_f32_e32 v30, v6, v7
	v_pk_mul_f32 v[6:7], v[26:27], v[68:69]
	v_pk_mul_f32 v[2:3], v[14:15], v[2:3]
	v_add_f32_e32 v6, v38, v6
	v_add_f32_e32 v3, v3, v37
	v_add_f32_e32 v6, v6, v7
	v_add_f32_e32 v7, v2, v3
	v_mov_b32_e32 v2, v20
	v_mov_b32_e32 v3, v28
	v_pk_mul_f32 v[2:3], v[2:3], v[8:9]
	v_mov_b32_e32 v28, v21
	v_add_f32_e32 v2, v36, v2
	v_add_f32_e32 v8, v2, v3
	v_mov_b32_e32 v2, v32
	v_mov_b32_e32 v3, v16
	v_pk_mul_f32 v[2:3], v[2:3], v[66:67]
	v_mov_b32_e32 v16, v33
	v_add_f32_e32 v3, v3, v35
	v_add_f32_e32 v9, v2, v3
	v_pk_mul_f32 v[2:3], v[28:29], v[64:65]
	s_nop 0
	v_add_f32_e32 v2, v34, v2
	v_add_f32_e32 v14, v2, v3
	v_pk_mul_f32 v[2:3], v[16:17], v[4:5]
	v_mul_f32_e32 v4, 0xbfb8aa3b, v8
	v_exp_f32_e32 v4, v4
	v_add_f32_e32 v0, v3, v0
	v_mul_f32_e32 v3, 0xbfb8aa3b, v6
	v_exp_f32_e32 v3, v3
	v_add_f32_e32 v4, 1.0, v4
	v_rcp_f32_e32 v4, v4
	v_add_f32_e32 v0, v2, v0
	v_add_f32_e32 v3, 1.0, v3
	v_rcp_f32_e32 v3, v3
	v_mul_f32_e32 v4, v8, v4
	v_mul_f32_e32 v8, 0xbfb8aa3b, v7
	v_exp_f32_e32 v8, v8
	v_mul_f32_e32 v2, 0xbfb8aa3b, v18
	v_mul_f32_e32 v3, v6, v3
	v_mul_f32_e32 v6, 0xbfb8aa3b, v30
	v_add_f32_e32 v8, 1.0, v8
	v_rcp_f32_e32 v8, v8
	v_exp_f32_e32 v2, v2
	v_mul_f32_e32 v5, 0xbfb8aa3b, v14
	v_exp_f32_e32 v6, v6
	v_mul_f32_e32 v7, v7, v8
	v_mul_f32_e32 v8, 0xbfb8aa3b, v9
	v_exp_f32_e32 v8, v8
	v_exp_f32_e32 v5, v5
	v_add_f32_e32 v2, 1.0, v2
	v_add_f32_e32 v6, 1.0, v6
	v_add_f32_e32 v8, 1.0, v8
	v_rcp_f32_e32 v8, v8
	v_rcp_f32_e32 v2, v2
	v_add_f32_e32 v5, 1.0, v5
	v_rcp_f32_e32 v6, v6
	v_mul_f32_e32 v8, v9, v8
	v_mul_f32_e32 v9, 0xbfb8aa3b, v0
	v_exp_f32_e32 v9, v9
	v_rcp_f32_e32 v5, v5
	v_mul_f32_e32 v2, v18, v2
	v_mul_f32_e32 v6, v30, v6
	v_add_f32_e32 v9, 1.0, v9
	v_rcp_f32_e32 v9, v9
	v_mul_f32_e32 v5, v14, v5
	v_cvt_pk_bf16_f32 v2, v2, v3
	v_cvt_pk_bf16_f32 v3, v4, v5
	v_mul_f32_e32 v0, v0, v9
	v_cvt_pk_bf16_f32 v4, v6, v7
	v_add_u32_e32 v6, s19, v54
	v_cvt_pk_bf16_f32 v5, v8, v0
	v_ashrrev_i32_e32 v7, 31, v6
	v_lshlrev_b32_e32 v0, 1, v56
	s_cbranch_scc1 .LBB0_226
	v_lshlrev_b64 v[8:9], 10, v[6:7]
	v_lshl_add_u64 v[8:9], s[14:15], 0, v[8:9]
	s_add_i32 s88, s22, 0xfffff600
	v_lshl_add_u64 v[8:9], s[88:89], 1, v[8:9]
	v_lshl_add_u64 v[8:9], v[8:9], 0, v[0:1]
	global_store_dwordx4 v[8:9], v[10:13], off

.LBB0_488:
	s_cmp_ge_i32 s66, s64
	s_cbranch_scc1 .LBB0_491
	v_add_u32_e32 v0, 64, v193
	v_xor_b32_e32 v2, 1, v192
	v_cmp_lt_i32_e32 vcc, v2, v0
	s_load_dwordx2 s[4:5], s[82:83], 0xd0
	v_lshlrev_b32_e32 v4, 3, v158
	v_cndmask_b32_e32 v2, v192, v2, vcc
	s_waitcnt vmcnt(0)
	v_lshlrev_b32_e32 v10, 2, v2
	v_xor_b32_e32 v2, 2, v192
	v_cmp_lt_i32_e32 vcc, v2, v0
	v_mov_b32_e32 v5, v1
	s_waitcnt lgkmcnt(0)
	v_lshl_add_u64 v[6:7], s[4:5], 0, v[4:5]
	v_cndmask_b32_e32 v2, v192, v2, vcc
	v_lshlrev_b32_e32 v11, 2, v2
	v_xor_b32_e32 v2, 4, v192
	v_cmp_lt_i32_e32 vcc, v2, v0
	s_mul_hi_i32 s3, s66, 0x300
	s_mul_i32 s6, s66, 0xc00
	v_cndmask_b32_e32 v2, v192, v2, vcc
	v_lshlrev_b32_e32 v12, 2, v2
	v_xor_b32_e32 v2, 8, v192
	v_cmp_lt_i32_e32 vcc, v2, v0
	v_mov_b32_e32 v8, 0xbb80200
	v_lshl_or_b32 v8, v158, 2, v8
	v_cndmask_b32_e32 v2, v192, v2, vcc
	v_lshlrev_b32_e32 v13, 2, v2
	v_xor_b32_e32 v2, 16, v192
	v_cmp_lt_i32_e32 vcc, v2, v0
	v_mov_b32_e32 v9, v1
	s_nop 0
	v_cndmask_b32_e32 v2, v192, v2, vcc
	v_lshlrev_b32_e32 v14, 2, v2
	v_xor_b32_e32 v2, 32, v192
	v_cmp_lt_i32_e32 vcc, v2, v0
	s_nop 1
	v_cndmask_b32_e32 v0, v192, v2, vcc
	v_lshlrev_b32_e32 v15, 2, v0
	v_lshlrev_b32_e32 v0, 4, v158
	v_lshl_add_u64 v[2:3], s[4:5], 0, v[0:1]
	s_mul_i32 s4, s66, 0x300
	s_add_u32 s4, s54, s4
	s_addc_u32 s5, s55, s3
	s_mul_hi_i32 s3, s66, 0xc00
	s_add_u32 s6, s54, s6
	s_addc_u32 s3, s55, s3
	s_add_u32 s6, s6, 0x11f80500
	s_addc_u32 s7, s3, 0
	s_mov_b32 s3, s66
	global_load_dwordx4 v[40:43], v[2:3], off
	global_load_dwordx2 v[44:45], v[6:7], off offset:1024
	v_add_co_u32_e32 v126, vcc, 0xbb80000, v4
	s_nop 1
	v_addc_co_u32_e32 v127, vcc, 0, v5, vcc
	s_mul_i32 s36, s1, 0xc00
	s_mul_i32 s48, s1, 0x300
.LBB0_490:
	s_mov_b32 s38, s3
	s_mov_b64 s[34:35], s[6:7]
	s_cmp_lt_i32 s38, s64
	s_cselect_b32 s98, s34, s6
	s_cselect_b32 s99, s35, s7
	v_lshl_add_u64 v[128:129], s[98:99], 0, v[0:1]
	global_load_dwordx4 v[48:51], v[128:129], off
	v_lshl_add_u64 v[128:129], s[98:99], 0, v[4:5]
	global_load_dwordx2 v[52:53], v[128:129], off offset:1024
	s_add_i32 s38, s38, s1
	s_add_u32 s34, s34, s36
	s_addc_u32 s35, s35, 0
	s_cmp_lt_i32 s38, s64
	s_cselect_b32 s98, s34, s6
	s_cselect_b32 s99, s35, s7
	v_lshl_add_u64 v[128:129], s[98:99], 0, v[0:1]
	global_load_dwordx4 v[56:59], v[128:129], off
	v_lshl_add_u64 v[128:129], s[98:99], 0, v[4:5]
	global_load_dwordx2 v[60:61], v[128:129], off offset:1024
	s_add_i32 s38, s38, s1
	s_add_u32 s34, s34, s36
	s_addc_u32 s35, s35, 0
	s_cmp_lt_i32 s38, s64
	s_cselect_b32 s98, s34, s6
	s_cselect_b32 s99, s35, s7
	v_lshl_add_u64 v[128:129], s[98:99], 0, v[0:1]
	global_load_dwordx4 v[64:67], v[128:129], off
	v_lshl_add_u64 v[128:129], s[98:99], 0, v[4:5]
	global_load_dwordx2 v[68:69], v[128:129], off offset:1024
	s_add_i32 s38, s38, s1
	s_add_u32 s34, s34, s36
	s_addc_u32 s35, s35, 0
	s_cmp_lt_i32 s38, s64
	s_cselect_b32 s98, s34, s6
	s_cselect_b32 s99, s35, s7
	v_lshl_add_u64 v[128:129], s[98:99], 0, v[0:1]
	global_load_dwordx4 v[72:75], v[128:129], off
	v_lshl_add_u64 v[128:129], s[98:99], 0, v[4:5]
	global_load_dwordx2 v[76:77], v[128:129], off offset:1024
	s_add_i32 s38, s38, s1
	s_add_u32 s34, s34, s36
	s_addc_u32 s35, s35, 0
	s_cmp_lt_i32 s38, s64
	s_cselect_b32 s98, s34, s6
	s_cselect_b32 s99, s35, s7
	v_lshl_add_u64 v[128:129], s[98:99], 0, v[0:1]
	global_load_dwordx4 v[80:83], v[128:129], off
	v_lshl_add_u64 v[128:129], s[98:99], 0, v[4:5]
	global_load_dwordx2 v[84:85], v[128:129], off offset:1024
	s_add_i32 s38, s38, s1
	s_add_u32 s34, s34, s36
	s_addc_u32 s35, s35, 0
	s_cmp_lt_i32 s38, s64
	s_cselect_b32 s98, s34, s6
	s_cselect_b32 s99, s35, s7
	v_lshl_add_u64 v[128:129], s[98:99], 0, v[0:1]
	global_load_dwordx4 v[88:91], v[128:129], off
	v_lshl_add_u64 v[128:129], s[98:99], 0, v[4:5]
	global_load_dwordx2 v[92:93], v[128:129], off offset:1024
	s_add_i32 s38, s38, s1
	s_add_u32 s34, s34, s36
	s_addc_u32 s35, s35, 0
	s_cmp_lt_i32 s38, s64
	s_cselect_b32 s98, s34, s6
	s_cselect_b32 s99, s35, s7
	v_lshl_add_u64 v[128:129], s[98:99], 0, v[0:1]
	global_load_dwordx4 v[96:99], v[128:129], off
	v_lshl_add_u64 v[128:129], s[98:99], 0, v[4:5]
	global_load_dwordx2 v[100:101], v[128:129], off offset:1024
	s_add_i32 s38, s38, s1
	s_add_u32 s34, s34, s36
	s_addc_u32 s35, s35, 0
	s_cmp_lt_i32 s38, s64
	s_cselect_b32 s98, s34, s6
	s_cselect_b32 s99, s35, s7
	v_lshl_add_u64 v[128:129], s[98:99], 0, v[0:1]
	global_load_dwordx4 v[104:107], v[128:129], off
	v_lshl_add_u64 v[128:129], s[98:99], 0, v[4:5]
	global_load_dwordx2 v[108:109], v[128:129], off offset:1024
	s_add_i32 s38, s38, s1
	s_add_u32 s34, s34, s36
	s_addc_u32 s35, s35, 0
	s_cmp_lt_i32 s38, s64
	s_cselect_b32 s98, s34, s6
	s_cselect_b32 s99, s35, s7
	v_lshl_add_u64 v[128:129], s[98:99], 0, v[0:1]
	global_load_dwordx4 v[112:115], v[128:129], off
	v_lshl_add_u64 v[128:129], s[98:99], 0, v[4:5]
	global_load_dwordx2 v[116:117], v[128:129], off offset:1024
	s_add_i32 s38, s38, s1
	s_add_u32 s34, s34, s36
	s_addc_u32 s35, s35, 0
	s_mov_b32 s38, s3
	s_mov_b64 s[46:47], s[4:5]
	s_cmp_lt_i32 s38, s64
	s_cbranch_scc0 .Lcq_rows_done
	s_waitcnt vmcnt(16)
	v_mul_f32_e32 v118, v49, v49
	v_fmac_f32_e32 v118, v48, v48
	v_fmac_f32_e32 v118, v50, v50
	v_fmac_f32_e32 v118, v51, v51
	v_fmac_f32_e32 v118, v52, v52
	v_fmac_f32_e32 v118, v53, v53
	s_nop 1
	v_add_f32_dpp v118, v118, v118 row_shr:1 row_mask:0xf bank_mask:0xf
	s_nop 1
	v_add_f32_dpp v118, v118, v118 row_shr:2 row_mask:0xf bank_mask:0xf
	s_nop 1
	v_add_f32_dpp v118, v118, v118 row_shr:4 row_mask:0xf bank_mask:0xf
	s_nop 1
	v_add_f32_dpp v118, v118, v118 row_shr:8 row_mask:0xf bank_mask:0xf
	s_nop 1
	v_add_f32_dpp v118, v118, v118 row_bcast:15 row_mask:0xa bank_mask:0xf
	s_nop 1
	v_add_f32_dpp v118, v118, v118 row_bcast:31 row_mask:0xc bank_mask:0xf
	s_nop 1
	v_readlane_b32 s37, v118, 63
	v_lshl_add_u64 v[122:123], s[46:47], 0, v[126:127]
	s_nop 1
	v_mov_b32_e32 v118, s37
	v_fmamk_f32 v118, v118, 0x3b2aaaab, v159
	v_cmp_gt_f32_e32 vcc, s85, v118
	v_mul_f32_e32 v119, 0x4b800000, v118
	s_nop 0
	v_cndmask_b32_e32 v118, v118, v119, vcc
	v_rsq_f32_e32 v118, v118
	s_nop 0
	v_mul_f32_e32 v119, 0x45800000, v118
	v_cndmask_b32_e32 v120, v118, v119, vcc
	v_mul_f32_e32 v48, v48, v120
	v_mul_f32_e32 v48, v40, v48
	v_mul_f32_e32 v49, v49, v120
	v_mul_f32_e32 v49, v41, v49
	v_mul_f32_e32 v50, v50, v120
	v_mul_f32_e32 v50, v42, v50
	v_mul_f32_e32 v51, v51, v120
	v_mul_f32_e32 v51, v43, v51
	v_cvt_pk_bf16_f32 v124, v48, v49
	v_cvt_pk_bf16_f32 v125, v50, v51
	global_store_dwordx2 v[122:123], v[124:125], off
	v_mul_f32_e32 v52, v52, v120
	v_mul_f32_e32 v52, v44, v52
	v_mul_f32_e32 v53, v53, v120
	v_mul_f32_e32 v53, v45, v53
	v_cvt_pk_bf16_f32 v119, v52, v53
	v_lshl_add_u64 v[122:123], s[46:47], 0, v[8:9]
	global_store_dword v[122:123], v119, off
	s_add_i32 s38, s38, s1
	s_add_u32 s46, s46, s48
	s_addc_u32 s47, s47, 0
	s_cmp_lt_i32 s38, s64
	s_cbranch_scc0 .Lcq_rows_done
	s_waitcnt vmcnt(16)
	v_mul_f32_e32 v118, v57, v57
	v_fmac_f32_e32 v118, v56, v56
	v_fmac_f32_e32 v118, v58, v58
	v_fmac_f32_e32 v118, v59, v59
	v_fmac_f32_e32 v118, v60, v60
	v_fmac_f32_e32 v118, v61, v61
	s_nop 1
	v_add_f32_dpp v118, v118, v118 row_shr:1 row_mask:0xf bank_mask:0xf
	s_nop 1
	v_add_f32_dpp v118, v118, v118 row_shr:2 row_mask:0xf bank_mask:0xf
	s_nop 1
	v_add_f32_dpp v118, v118, v118 row_shr:4 row_mask:0xf bank_mask:0xf
	s_nop 1
	v_add_f32_dpp v118, v118, v118 row_shr:8 row_mask:0xf bank_mask:0xf
	s_nop 1
	v_add_f32_dpp v118, v118, v118 row_bcast:15 row_mask:0xa bank_mask:0xf
	s_nop 1
	v_add_f32_dpp v118, v118, v118 row_bcast:31 row_mask:0xc bank_mask:0xf
	s_nop 1
	v_readlane_b32 s37, v118, 63
	v_lshl_add_u64 v[122:123], s[46:47], 0, v[126:127]
	s_nop 1
	v_mov_b32_e32 v118, s37
	v_fmamk_f32 v118, v118, 0x3b2aaaab, v159
	v_cmp_gt_f32_e32 vcc, s85, v118
	v_mul_f32_e32 v119, 0x4b800000, v118
	s_nop 0
	v_cndmask_b32_e32 v118, v118, v119, vcc
	v_rsq_f32_e32 v118, v118
	s_nop 0
	v_mul_f32_e32 v119, 0x45800000, v118
	v_cndmask_b32_e32 v120, v118, v119, vcc
	v_mul_f32_e32 v56, v56, v120
	v_mul_f32_e32 v56, v40, v56
	v_mul_f32_e32 v57, v57, v120
	v_mul_f32_e32 v57, v41, v57
	v_mul_f32_e32 v58, v58, v120
	v_mul_f32_e32 v58, v42, v58
	v_mul_f32_e32 v59, v59, v120
	v_mul_f32_e32 v59, v43, v59
	v_cvt_pk_bf16_f32 v124, v56, v57
	v_cvt_pk_bf16_f32 v125, v58, v59
	global_store_dwordx2 v[122:123], v[124:125], off
	v_mul_f32_e32 v60, v60, v120
	v_mul_f32_e32 v60, v44, v60
	v_mul_f32_e32 v61, v61, v120
	v_mul_f32_e32 v61, v45, v61
	v_cvt_pk_bf16_f32 v119, v60, v61
	v_lshl_add_u64 v[122:123], s[46:47], 0, v[8:9]
	global_store_dword v[122:123], v119, off
	s_add_i32 s38, s38, s1
	s_add_u32 s46, s46, s48
	s_addc_u32 s47, s47, 0
	s_cmp_lt_i32 s38, s64
	s_cbranch_scc0 .Lcq_rows_done
	s_waitcnt vmcnt(16)
	v_mul_f32_e32 v118, v65, v65
	v_fmac_f32_e32 v118, v64, v64
	v_fmac_f32_e32 v118, v66, v66
	v_fmac_f32_e32 v118, v67, v67
	v_fmac_f32_e32 v118, v68, v68
	v_fmac_f32_e32 v118, v69, v69
	s_nop 1
	v_add_f32_dpp v118, v118, v118 row_shr:1 row_mask:0xf bank_mask:0xf
	s_nop 1
	v_add_f32_dpp v118, v118, v118 row_shr:2 row_mask:0xf bank_mask:0xf
	s_nop 1
	v_add_f32_dpp v118, v118, v118 row_shr:4 row_mask:0xf bank_mask:0xf
	s_nop 1
	v_add_f32_dpp v118, v118, v118 row_shr:8 row_mask:0xf bank_mask:0xf
	s_nop 1
	v_add_f32_dpp v118, v118, v118 row_bcast:15 row_mask:0xa bank_mask:0xf
	s_nop 1
	v_add_f32_dpp v118, v118, v118 row_bcast:31 row_mask:0xc bank_mask:0xf
	s_nop 1
	v_readlane_b32 s37, v118, 63
	v_lshl_add_u64 v[122:123], s[46:47], 0, v[126:127]
	s_nop 1
	v_mov_b32_e32 v118, s37
	v_fmamk_f32 v118, v118, 0x3b2aaaab, v159
	v_cmp_gt_f32_e32 vcc, s85, v118
	v_mul_f32_e32 v119, 0x4b800000, v118
	s_nop 0
	v_cndmask_b32_e32 v118, v118, v119, vcc
	v_rsq_f32_e32 v118, v118
	s_nop 0
	v_mul_f32_e32 v119, 0x45800000, v118
	v_cndmask_b32_e32 v120, v118, v119, vcc
	v_mul_f32_e32 v64, v64, v120
	v_mul_f32_e32 v64, v40, v64
	v_mul_f32_e32 v65, v65, v120
	v_mul_f32_e32 v65, v41, v65
	v_mul_f32_e32 v66, v66, v120
	v_mul_f32_e32 v66, v42, v66
	v_mul_f32_e32 v67, v67, v120
	v_mul_f32_e32 v67, v43, v67
	v_cvt_pk_bf16_f32 v124, v64, v65
	v_cvt_pk_bf16_f32 v125, v66, v67
	global_store_dwordx2 v[122:123], v[124:125], off
	v_mul_f32_e32 v68, v68, v120
	v_mul_f32_e32 v68, v44, v68
	v_mul_f32_e32 v69, v69, v120
	v_mul_f32_e32 v69, v45, v69
	v_cvt_pk_bf16_f32 v119, v68, v69
	v_lshl_add_u64 v[122:123], s[46:47], 0, v[8:9]
	global_store_dword v[122:123], v119, off
	s_add_i32 s38, s38, s1
	s_add_u32 s46, s46, s48
	s_addc_u32 s47, s47, 0
	s_cmp_lt_i32 s38, s64
	s_cbranch_scc0 .Lcq_rows_done
	s_waitcnt vmcnt(16)
	v_mul_f32_e32 v118, v73, v73
	v_fmac_f32_e32 v118, v72, v72
	v_fmac_f32_e32 v118, v74, v74
	v_fmac_f32_e32 v118, v75, v75
	v_fmac_f32_e32 v118, v76, v76
	v_fmac_f32_e32 v118, v77, v77
	s_nop 1
	v_add_f32_dpp v118, v118, v118 row_shr:1 row_mask:0xf bank_mask:0xf
	s_nop 1
	v_add_f32_dpp v118, v118, v118 row_shr:2 row_mask:0xf bank_mask:0xf
	s_nop 1
	v_add_f32_dpp v118, v118, v118 row_shr:4 row_mask:0xf bank_mask:0xf
	s_nop 1
	v_add_f32_dpp v118, v118, v118 row_shr:8 row_mask:0xf bank_mask:0xf
	s_nop 1
	v_add_f32_dpp v118, v118, v118 row_bcast:15 row_mask:0xa bank_mask:0xf
	s_nop 1
	v_add_f32_dpp v118, v118, v118 row_bcast:31 row_mask:0xc bank_mask:0xf
	s_nop 1
	v_readlane_b32 s37, v118, 63
	v_lshl_add_u64 v[122:123], s[46:47], 0, v[126:127]
	s_nop 1
	v_mov_b32_e32 v118, s37
	v_fmamk_f32 v118, v118, 0x3b2aaaab, v159
	v_cmp_gt_f32_e32 vcc, s85, v118
	v_mul_f32_e32 v119, 0x4b800000, v118
	s_nop 0
	v_cndmask_b32_e32 v118, v118, v119, vcc
	v_rsq_f32_e32 v118, v118
	s_nop 0
	v_mul_f32_e32 v119, 0x45800000, v118
	v_cndmask_b32_e32 v120, v118, v119, vcc
	v_mul_f32_e32 v72, v72, v120
	v_mul_f32_e32 v72, v40, v72
	v_mul_f32_e32 v73, v73, v120
	v_mul_f32_e32 v73, v41, v73
	v_mul_f32_e32 v74, v74, v120
	v_mul_f32_e32 v74, v42, v74
	v_mul_f32_e32 v75, v75, v120
	v_mul_f32_e32 v75, v43, v75
	v_cvt_pk_bf16_f32 v124, v72, v73
	v_cvt_pk_bf16_f32 v125, v74, v75
	global_store_dwordx2 v[122:123], v[124:125], off
	v_mul_f32_e32 v76, v76, v120
	v_mul_f32_e32 v76, v44, v76
	v_mul_f32_e32 v77, v77, v120
	v_mul_f32_e32 v77, v45, v77
	v_cvt_pk_bf16_f32 v119, v76, v77
	v_lshl_add_u64 v[122:123], s[46:47], 0, v[8:9]
	global_store_dword v[122:123], v119, off
	s_add_i32 s38, s38, s1
	s_add_u32 s46, s46, s48
	s_addc_u32 s47, s47, 0
	s_cmp_lt_i32 s38, s64
	s_cbranch_scc0 .Lcq_rows_done
	s_waitcnt vmcnt(16)
	v_mul_f32_e32 v118, v81, v81
	v_fmac_f32_e32 v118, v80, v80
	v_fmac_f32_e32 v118, v82, v82
	v_fmac_f32_e32 v118, v83, v83
	v_fmac_f32_e32 v118, v84, v84
	v_fmac_f32_e32 v118, v85, v85
	s_nop 1
	v_add_f32_dpp v118, v118, v118 row_shr:1 row_mask:0xf bank_mask:0xf
	s_nop 1
	v_add_f32_dpp v118, v118, v118 row_shr:2 row_mask:0xf bank_mask:0xf
	s_nop 1
	v_add_f32_dpp v118, v118, v118 row_shr:4 row_mask:0xf bank_mask:0xf
	s_nop 1
	v_add_f32_dpp v118, v118, v118 row_shr:8 row_mask:0xf bank_mask:0xf
	s_nop 1
	v_add_f32_dpp v118, v118, v118 row_bcast:15 row_mask:0xa bank_mask:0xf
	s_nop 1
	v_add_f32_dpp v118, v118, v118 row_bcast:31 row_mask:0xc bank_mask:0xf
	s_nop 1
	v_readlane_b32 s37, v118, 63
	v_lshl_add_u64 v[122:123], s[46:47], 0, v[126:127]
	s_nop 1
	v_mov_b32_e32 v118, s37
	v_fmamk_f32 v118, v118, 0x3b2aaaab, v159
	v_cmp_gt_f32_e32 vcc, s85, v118
	v_mul_f32_e32 v119, 0x4b800000, v118
	s_nop 0
	v_cndmask_b32_e32 v118, v118, v119, vcc
	v_rsq_f32_e32 v118, v118
	s_nop 0
	v_mul_f32_e32 v119, 0x45800000, v118
	v_cndmask_b32_e32 v120, v118, v119, vcc
	v_mul_f32_e32 v80, v80, v120
	v_mul_f32_e32 v80, v40, v80
	v_mul_f32_e32 v81, v81, v120
	v_mul_f32_e32 v81, v41, v81
	v_mul_f32_e32 v82, v82, v120
	v_mul_f32_e32 v82, v42, v82
	v_mul_f32_e32 v83, v83, v120
	v_mul_f32_e32 v83, v43, v83
	v_cvt_pk_bf16_f32 v124, v80, v81
	v_cvt_pk_bf16_f32 v125, v82, v83
	global_store_dwordx2 v[122:123], v[124:125], off
	v_mul_f32_e32 v84, v84, v120
	v_mul_f32_e32 v84, v44, v84
	v_mul_f32_e32 v85, v85, v120
	v_mul_f32_e32 v85, v45, v85
	v_cvt_pk_bf16_f32 v119, v84, v85
	v_lshl_add_u64 v[122:123], s[46:47], 0, v[8:9]
	global_store_dword v[122:123], v119, off
	s_add_i32 s38, s38, s1
	s_add_u32 s46, s46, s48
	s_addc_u32 s47, s47, 0
	s_cmp_lt_i32 s38, s64
	s_cbranch_scc0 .Lcq_rows_done
	s_waitcnt vmcnt(16)
	v_mul_f32_e32 v118, v89, v89
	v_fmac_f32_e32 v118, v88, v88
	v_fmac_f32_e32 v118, v90, v90
	v_fmac_f32_e32 v118, v91, v91
	v_fmac_f32_e32 v118, v92, v92
	v_fmac_f32_e32 v118, v93, v93
	s_nop 1
	v_add_f32_dpp v118, v118, v118 row_shr:1 row_mask:0xf bank_mask:0xf
	s_nop 1
	v_add_f32_dpp v118, v118, v118 row_shr:2 row_mask:0xf bank_mask:0xf
	s_nop 1
	v_add_f32_dpp v118, v118, v118 row_shr:4 row_mask:0xf bank_mask:0xf
	s_nop 1
	v_add_f32_dpp v118, v118, v118 row_shr:8 row_mask:0xf bank_mask:0xf
	s_nop 1
	v_add_f32_dpp v118, v118, v118 row_bcast:15 row_mask:0xa bank_mask:0xf
	s_nop 1
	v_add_f32_dpp v118, v118, v118 row_bcast:31 row_mask:0xc bank_mask:0xf
	s_nop 1
	v_readlane_b32 s37, v118, 63
	v_lshl_add_u64 v[122:123], s[46:47], 0, v[126:127]
	s_nop 1
	v_mov_b32_e32 v118, s37
	v_fmamk_f32 v118, v118, 0x3b2aaaab, v159
	v_cmp_gt_f32_e32 vcc, s85, v118
	v_mul_f32_e32 v119, 0x4b800000, v118
	s_nop 0
	v_cndmask_b32_e32 v118, v118, v119, vcc
	v_rsq_f32_e32 v118, v118
	s_nop 0
	v_mul_f32_e32 v119, 0x45800000, v118
	v_cndmask_b32_e32 v120, v118, v119, vcc
	v_mul_f32_e32 v88, v88, v120
	v_mul_f32_e32 v88, v40, v88
	v_mul_f32_e32 v89, v89, v120
	v_mul_f32_e32 v89, v41, v89
	v_mul_f32_e32 v90, v90, v120
	v_mul_f32_e32 v90, v42, v90
	v_mul_f32_e32 v91, v91, v120
	v_mul_f32_e32 v91, v43, v91
	v_cvt_pk_bf16_f32 v124, v88, v89
	v_cvt_pk_bf16_f32 v125, v90, v91
	global_store_dwordx2 v[122:123], v[124:125], off
	v_mul_f32_e32 v92, v92, v120
	v_mul_f32_e32 v92, v44, v92
	v_mul_f32_e32 v93, v93, v120
	v_mul_f32_e32 v93, v45, v93
	v_cvt_pk_bf16_f32 v119, v92, v93
	v_lshl_add_u64 v[122:123], s[46:47], 0, v[8:9]
	global_store_dword v[122:123], v119, off
	s_add_i32 s38, s38, s1
	s_add_u32 s46, s46, s48
	s_addc_u32 s47, s47, 0
	s_cmp_lt_i32 s38, s64
	s_cbranch_scc0 .Lcq_rows_done
	s_waitcnt vmcnt(16)
	v_mul_f32_e32 v118, v97, v97
	v_fmac_f32_e32 v118, v96, v96
	v_fmac_f32_e32 v118, v98, v98
	v_fmac_f32_e32 v118, v99, v99
	v_fmac_f32_e32 v118, v100, v100
	v_fmac_f32_e32 v118, v101, v101
	s_nop 1
	v_add_f32_dpp v118, v118, v118 row_shr:1 row_mask:0xf bank_mask:0xf
	s_nop 1
	v_add_f32_dpp v118, v118, v118 row_shr:2 row_mask:0xf bank_mask:0xf
	s_nop 1
	v_add_f32_dpp v118, v118, v118 row_shr:4 row_mask:0xf bank_mask:0xf
	s_nop 1
	v_add_f32_dpp v118, v118, v118 row_shr:8 row_mask:0xf bank_mask:0xf
	s_nop 1
	v_add_f32_dpp v118, v118, v118 row_bcast:15 row_mask:0xa bank_mask:0xf
	s_nop 1
	v_add_f32_dpp v118, v118, v118 row_bcast:31 row_mask:0xc bank_mask:0xf
	s_nop 1
	v_readlane_b32 s37, v118, 63
	v_lshl_add_u64 v[122:123], s[46:47], 0, v[126:127]
	s_nop 1
	v_mov_b32_e32 v118, s37
	v_fmamk_f32 v118, v118, 0x3b2aaaab, v159
	v_cmp_gt_f32_e32 vcc, s85, v118
	v_mul_f32_e32 v119, 0x4b800000, v118
	s_nop 0
	v_cndmask_b32_e32 v118, v118, v119, vcc
	v_rsq_f32_e32 v118, v118
	s_nop 0
	v_mul_f32_e32 v119, 0x45800000, v118
	v_cndmask_b32_e32 v120, v118, v119, vcc
	v_mul_f32_e32 v96, v96, v120
	v_mul_f32_e32 v96, v40, v96
	v_mul_f32_e32 v97, v97, v120
	v_mul_f32_e32 v97, v41, v97
	v_mul_f32_e32 v98, v98, v120
	v_mul_f32_e32 v98, v42, v98
	v_mul_f32_e32 v99, v99, v120
	v_mul_f32_e32 v99, v43, v99
	v_cvt_pk_bf16_f32 v124, v96, v97
	v_cvt_pk_bf16_f32 v125, v98, v99
	global_store_dwordx2 v[122:123], v[124:125], off
	v_mul_f32_e32 v100, v100, v120
	v_mul_f32_e32 v100, v44, v100
	v_mul_f32_e32 v101, v101, v120
	v_mul_f32_e32 v101, v45, v101
	v_cvt_pk_bf16_f32 v119, v100, v101
	v_lshl_add_u64 v[122:123], s[46:47], 0, v[8:9]
	global_store_dword v[122:123], v119, off
	s_add_i32 s38, s38, s1
	s_add_u32 s46, s46, s48
	s_addc_u32 s47, s47, 0
	s_cmp_lt_i32 s38, s64
	s_cbranch_scc0 .Lcq_rows_done
	s_waitcnt vmcnt(16)
	v_mul_f32_e32 v118, v105, v105
	v_fmac_f32_e32 v118, v104, v104
	v_fmac_f32_e32 v118, v106, v106
	v_fmac_f32_e32 v118, v107, v107
	v_fmac_f32_e32 v118, v108, v108
	v_fmac_f32_e32 v118, v109, v109
	s_nop 1
	v_add_f32_dpp v118, v118, v118 row_shr:1 row_mask:0xf bank_mask:0xf
	s_nop 1
	v_add_f32_dpp v118, v118, v118 row_shr:2 row_mask:0xf bank_mask:0xf
	s_nop 1
	v_add_f32_dpp v118, v118, v118 row_shr:4 row_mask:0xf bank_mask:0xf
	s_nop 1
	v_add_f32_dpp v118, v118, v118 row_shr:8 row_mask:0xf bank_mask:0xf
	s_nop 1
	v_add_f32_dpp v118, v118, v118 row_bcast:15 row_mask:0xa bank_mask:0xf
	s_nop 1
	v_add_f32_dpp v118, v118, v118 row_bcast:31 row_mask:0xc bank_mask:0xf
	s_nop 1
	v_readlane_b32 s37, v118, 63
	v_lshl_add_u64 v[122:123], s[46:47], 0, v[126:127]
	s_nop 1
	v_mov_b32_e32 v118, s37
	v_fmamk_f32 v118, v118, 0x3b2aaaab, v159
	v_cmp_gt_f32_e32 vcc, s85, v118
	v_mul_f32_e32 v119, 0x4b800000, v118
	s_nop 0
	v_cndmask_b32_e32 v118, v118, v119, vcc
	v_rsq_f32_e32 v118, v118
	s_nop 0
	v_mul_f32_e32 v119, 0x45800000, v118
	v_cndmask_b32_e32 v120, v118, v119, vcc
	v_mul_f32_e32 v104, v104, v120
	v_mul_f32_e32 v104, v40, v104
	v_mul_f32_e32 v105, v105, v120
	v_mul_f32_e32 v105, v41, v105
	v_mul_f32_e32 v106, v106, v120
	v_mul_f32_e32 v106, v42, v106
	v_mul_f32_e32 v107, v107, v120
	v_mul_f32_e32 v107, v43, v107
	v_cvt_pk_bf16_f32 v124, v104, v105
	v_cvt_pk_bf16_f32 v125, v106, v107
	global_store_dwordx2 v[122:123], v[124:125], off
	v_mul_f32_e32 v108, v108, v120
	v_mul_f32_e32 v108, v44, v108
	v_mul_f32_e32 v109, v109, v120
	v_mul_f32_e32 v109, v45, v109
	v_cvt_pk_bf16_f32 v119, v108, v109
	v_lshl_add_u64 v[122:123], s[46:47], 0, v[8:9]
	global_store_dword v[122:123], v119, off
	s_add_i32 s38, s38, s1
	s_add_u32 s46, s46, s48
	s_addc_u32 s47, s47, 0
	s_cmp_lt_i32 s38, s64
	s_cbranch_scc0 .Lcq_rows_done
	s_waitcnt vmcnt(16)
	v_mul_f32_e32 v118, v113, v113
	v_fmac_f32_e32 v118, v112, v112
	v_fmac_f32_e32 v118, v114, v114
	v_fmac_f32_e32 v118, v115, v115
	v_fmac_f32_e32 v118, v116, v116
	v_fmac_f32_e32 v118, v117, v117
	s_nop 1
	v_add_f32_dpp v118, v118, v118 row_shr:1 row_mask:0xf bank_mask:0xf
	s_nop 1
	v_add_f32_dpp v118, v118, v118 row_shr:2 row_mask:0xf bank_mask:0xf
	s_nop 1
	v_add_f32_dpp v118, v118, v118 row_shr:4 row_mask:0xf bank_mask:0xf
	s_nop 1
	v_add_f32_dpp v118, v118, v118 row_shr:8 row_mask:0xf bank_mask:0xf
	s_nop 1
	v_add_f32_dpp v118, v118, v118 row_bcast:15 row_mask:0xa bank_mask:0xf
	s_nop 1
	v_add_f32_dpp v118, v118, v118 row_bcast:31 row_mask:0xc bank_mask:0xf
	s_nop 1
	v_readlane_b32 s37, v118, 63
	v_lshl_add_u64 v[122:123], s[46:47], 0, v[126:127]
	s_nop 1
	v_mov_b32_e32 v118, s37
	v_fmamk_f32 v118, v118, 0x3b2aaaab, v159
	v_cmp_gt_f32_e32 vcc, s85, v118
	v_mul_f32_e32 v119, 0x4b800000, v118
	s_nop 0
	v_cndmask_b32_e32 v118, v118, v119, vcc
	v_rsq_f32_e32 v118, v118
	s_nop 0
	v_mul_f32_e32 v119, 0x45800000, v118
	v_cndmask_b32_e32 v120, v118, v119, vcc
	v_mul_f32_e32 v112, v112, v120
	v_mul_f32_e32 v112, v40, v112
	v_mul_f32_e32 v113, v113, v120
	v_mul_f32_e32 v113, v41, v113
	v_mul_f32_e32 v114, v114, v120
	v_mul_f32_e32 v114, v42, v114
	v_mul_f32_e32 v115, v115, v120
	v_mul_f32_e32 v115, v43, v115
	v_cvt_pk_bf16_f32 v124, v112, v113
	v_cvt_pk_bf16_f32 v125, v114, v115
	global_store_dwordx2 v[122:123], v[124:125], off
	v_mul_f32_e32 v116, v116, v120
	v_mul_f32_e32 v116, v44, v116
	v_mul_f32_e32 v117, v117, v120
	v_mul_f32_e32 v117, v45, v117
	v_cvt_pk_bf16_f32 v119, v116, v117
	v_lshl_add_u64 v[122:123], s[46:47], 0, v[8:9]
	global_store_dword v[122:123], v119, off
	s_add_i32 s38, s38, s1
	s_add_u32 s46, s46, s48
	s_addc_u32 s47, s47, 0
.Lcq_rows_done:
	s_mul_i32 s37, s1, 9
	s_add_i32 s3, s3, s37
	s_mul_i32 s37, s36, 9
	s_add_u32 s6, s6, s37
	s_addc_u32 s7, s7, 0
	s_mul_i32 s37, s48, 9
	s_add_u32 s4, s4, s37
	s_addc_u32 s5, s5, 0
	s_cmp_ge_i32 s3, s64
	s_cbranch_scc0 .LBB0_490
